# A-unit prologue waits for outstanding stores only after a non-attention unit (16-byte code shift keeps the instruction-stream phase of the hot loops)
# baseline (speedup 1.0000x reference)
; template <bool TRACK> ...
;     ...
;     const int srow = tid >> 3, sc = tid & 7;
;     u32x4 kreg, vreg;
;     { const int tl = 0 < n0 ? 0 : t1lo; kreg = *(const u32x4*)(Kb + (size_t)(tl * 64 + srow) * 64 + sc * 8); vreg = *(const u32x4*)(Vtb + (size_t)srow * KEYS + tl * 64 + sc * 8); }
;     bf16x8 qf[4];
;     { const int qrow = wave * 32 + r32; const bf16* qp = Qraw + (size_t)qrow * INW + hi * 8;
;       float qv[4][8]; float ss = 0.f;
; #pragma unroll
;       for (int d = 0; d < 4; ++d) { unpack8(*(const u32x4*)(qp + d * 16), qv[d]);
; template <int PH_EN_T>
; __device__ __forceinline__ void p3_mixers(const Params& p, LAS unsigned char* lds, int l, const int tid_in, const int lane_in, int wave, int G) {
;     ...
;             const bool isC = u >= 1792; const int v = u - (isC ? 1792 : 256), b = v / 48, rem = v % 48, h = rem >> 3, qb = rem & 7, kvh = h / 3;
;             const float* ropet = (const float*)(p.ws + WS_ROPE); const float* qnw = (isC ? p.qn_c : p.qn_a) + l * 64;
;             const bf16* Kb = (const bf16*)(p.ws + (isC ? WS_KC : WS_KA)) + (size_t)(b * 2 + kvh) * KEYS * 64;
;             const bf16* Vt = (const bf16*)(p.ws + (isC ? WS_VCT : WS_VAT)) + (size_t)(b * 2 + kvh) * 64 * KEYS;
;             const size_t row0 = (size_t)b * 2048 + qb * 256;
;             if (!isC) { for (int rep = 0; rep < 1 + ((REP_UNIT >> 1) & 1); ++rep) { if (ntA) attn_unit<false>(lds, PROJ + row0 * INW + h * 64, qnw, ropet, qb * 256, Kb, Vt, 36, 0, 0, 0, false, 0.f, 0.f, PROJ + row0 * INW + 640 + h * 64, MIX + row0 * DM + h * 64, tid, lane, wave);
.LBB0_154:
	s_andn2_b64 vcc, exec, s[20:21]
	s_cbranch_vccnz .LBB0_206
	s_cmpk_gt_u32 s62, 0x6ff
	s_cselect_b64 s[20:21], -1, 0
	s_and_b64 vcc, s[20:21], exec
	s_mov_b32 s4, 0x32600000
	s_cselect_b32 s45, s4, 0x31400000
	s_mov_b32 s4, 0x30200000
	s_mov_b32 s20, 0xf900
	s_cselect_b32 s50, s4, 0x2f000000
	v_readlane_b32 s4, v249, 19
	s_cselect_b32 s20, s20, 0xff00
	v_readlane_b32 s6, v249, 21
	v_readlane_b32 s7, v249, 22
	v_readlane_b32 s10, v249, 25
	v_readlane_b32 s11, v249, 26
	s_cselect_b32 s25, s11, s7
	s_cselect_b32 s27, s10, s6
	s_add_i32 s20, s20, s62
	s_and_b32 s21, s20, 0xffff
	s_mul_i32 s21, s21, 0xaaab
	s_lshr_b32 s34, s21, 21
	s_mul_i32 s21, s34, 48
	s_sub_i32 s20, s20, s21
	s_and_b32 s21, s20, 0xffff
	s_bfe_u32 s24, s20, 0xd0003
	s_and_b32 s26, s20, 7
	s_cmp_gt_u32 s21, 23
	s_cselect_b64 s[20:21], -1, 0
	s_lshl_b64 s[22:23], s[96:97], 2
	s_add_u32 s42, s27, s22
	s_addc_u32 s43, s25, s23
	v_readlane_b32 s76, v251, 0
	v_readlane_b32 s77, v251, 1
	s_add_u32 s22, s76, s50
	v_cndmask_b32_e64 v0, 0, 1, s[20:21]
	s_addc_u32 s23, s77, 0
	s_lshl_b32 s51, s34, 1
	v_readfirstlane_b32 s73, v0
	s_or_b32 s20, s51, s73
	s_and_b32 s20, s20, 0xfff
	s_mul_i32 s20, s20, 0x48000
	s_add_u32 s40, s22, s20
	s_addc_u32 s41, s23, 0
	s_add_u32 s21, s76, s45
	s_addc_u32 s22, s77, 0
	s_add_u32 s46, s21, s20
	s_addc_u32 s47, s22, 0
	s_lshl_b32 s20, s34, 11
	s_lshl_b32 s25, s26, 8
	s_or_b32 s34, s20, s25
	v_lshrrev_b32_e32 v194, 3, v189
	v_or_b32_e32 v0, 32, v191
	v_and_b32_e32 v2, 7, v190
	v_lshrrev_b32_e32 v3, 3, v191
	s_mov_b64 s[20:21], -1
	v_and_b32_e32 v124, 32, v191
	s_mul_hi_u32 s27, s34, 0x1800
	s_mul_i32 s44, s34, 0x1800
	v_mul_u32_u24_e32 v197, 0x900, v194
	v_lshlrev_b32_e32 v196, 2, v194
	v_mul_u32_u24_e32 v195, 0x48, v0
	v_lshl_add_u32 v192, v2, 5, s65
	v_lshlrev_b32_e32 v134, 4, v2
	v_or_b32_e32 v132, s64, v3
	v_mul_u32_u24_e32 v193, 0x110, v3
	v_or_b32_e32 v130, s70, v3
	v_or_b32_e32 v128, s71, v3
	v_or_b32_e32 v126, s72, v3
	v_lshlrev_b32_e32 v122, 7, v194
	v_readlane_b32 s5, v249, 20
	v_readlane_b32 s8, v249, 23
	v_readlane_b32 s9, v249, 24
	v_readlane_b32 s12, v249, 27
	v_readlane_b32 s13, v249, 28
	v_readlane_b32 s14, v249, 29
	v_readlane_b32 s15, v249, 30
	v_readlane_b32 s16, v249, 31
	v_readlane_b32 s17, v249, 32
	v_readlane_b32 s18, v249, 33
	v_readlane_b32 s19, v249, 34
	v_readlane_b32 s78, v251, 2
	v_readlane_b32 s79, v251, 3
	s_cbranch_vccnz .LBB0_170
	v_readlane_b32 s20, v252, 20
	v_readlane_b32 s21, v252, 21
	s_add_u32 s20, s20, s44
	s_addc_u32 s21, s21, s27
	s_lshl_b32 s48, s24, 7
	s_add_u32 s20, s20, s48
	v_lshlrev_b32_e32 v0, 3, v189
	s_addc_u32 s21, s21, 0
	s_lshl_b64 s[22:23], s[34:35], 11
	v_readlane_b32 s74, v250, 55
	v_and_b32_e32 v9, 56, v0
	v_lshlrev_b32_e32 v0, 1, v197
	v_readlane_b32 s75, v250, 56
	s_add_u32 s22, s74, s22
	v_lshl_add_u64 v[4:5], s[46:47], 0, v[0:1]
	v_lshlrev_b32_e32 v2, 1, v9
	v_mov_b32_e32 v3, v1
	s_movk_i32 s4, 0x48
	s_addc_u32 s23, s75, s23
	v_lshl_add_u64 v[6:7], v[4:5], 0, v[2:3]
	v_mad_u32_u24 v4, v194, s4, v9
	s_nop 0
	s_sub_i32 s4, s62, s59
	s_cmpk_lt_i32 s4, 0x100
	s_cbranch_scc0 .Lskip_drain_a
	s_waitcnt vmcnt(0)
.Lskip_drain_a:
	s_add_u32 s22, s22, s48
	v_and_b32_e32 v12, 31, v190
	v_lshrrev_b32_e32 v8, 5, v191
	v_lshlrev_b32_e32 v201, 1, v4
	v_sub_u32_e32 v4, v4, v196
	s_addc_u32 s23, s23, 0
	v_lshlrev_b32_e32 v199, 3, v8
	v_lshlrev_b32_e32 v203, 1, v4
	v_mul_u32_u24_e32 v4, 0x48, v12
	v_mov_b32_e32 v135, v1
	v_mov_b32_e32 v133, v1
	v_add_lshl_u32 v204, v199, v4, 1
	v_lshlrev_b32_e32 v156, 4, v8
	v_mov_b32_e32 v4, s65
	s_movk_i32 s4, 0x110
	v_lshl_add_u64 v[8:9], s[22:23], 0, v[134:135]
	v_lshlrev_b64 v[10:11], 11, v[132:133]
	v_mov_b32_e32 v131, v1
	v_mad_u32_u24 v198, v12, s4, v4
	v_lshl_add_u64 v[4:5], s[20:21], 0, v[134:135]
	v_lshl_add_u64 v[152:153], v[8:9], 0, v[10:11]
	v_lshlrev_b64 v[10:11], 11, v[130:131]
	v_mov_b32_e32 v129, v1
	v_mov_b32_e32 v127, v1
	v_mad_u64_u32 v[154:155], s[22:23], v132, s29, v[4:5]
	v_mad_u64_u32 v[150:151], s[22:23], v130, s29, v[4:5]
	v_lshl_add_u64 v[144:145], v[8:9], 0, v[10:11]
	v_mad_u64_u32 v[142:143], s[22:23], v128, s29, v[4:5]
	v_lshlrev_b64 v[10:11], 11, v[128:129]
	v_mad_u64_u32 v[138:139], s[22:23], v126, s29, v[4:5]
	v_lshlrev_b64 v[4:5], 11, v[126:127]
	v_lshl_add_u64 v[140:141], v[8:9], 0, v[10:11]
	v_lshl_add_u64 v[136:137], v[8:9], 0, v[4:5]
	v_or_b32_e32 v8, s64, v12
	v_add_u32_e32 v4, s25, v8
	v_mov_b32_e32 v5, v1
	v_readlane_b32 s22, v252, 26
	v_lshlrev_b64 v[4:5], 7, v[4:5]
	v_readlane_b32 s23, v252, 27
	v_mov_b32_e32 v125, v1
	v_mov_b32_e32 v157, v1
	v_lshl_add_u64 v[4:5], s[22:23], 0, v[4:5]
	v_lshl_add_u64 v[22:23], v[4:5], 0, v[124:125]
	v_mov_b64_e32 v[4:5], s[20:21]
	v_mad_u64_u32 v[4:5], s[20:21], v8, s29, v[4:5]
	v_mov_b32_e32 v123, v1
	v_lshl_add_u64 v[26:27], v[4:5], 0, v[156:157]
	v_lshl_add_u64 v[4:5], s[40:41], 0, v[122:123]
	v_lshl_add_u64 v[2:3], v[4:5], 0, v[2:3]
	v_mul_u32_u24_e32 v200, 0x88, v12
	global_load_dwordx4 v[2:5], v[2:3], off
	s_nop 0
	global_load_dwordx4 v[6:9], v[6:7], off
	s_nop 0
	global_load_dwordx4 v[10:13], v[26:27], off
	global_load_dwordx4 v[18:21], v[26:27], off offset:32
	s_mov_b64 s[4:5], 0x40040
	v_lshl_add_u64 v[42:43], v[22:23], 0, s[4:5]
	s_mov_b64 s[4:5], 0x40000
	s_waitcnt vmcnt(4)
	v_lshl_add_u64 v[14:15], v[22:23], 0, s[4:5]
	v_readlane_b32 s4, v248, 9
	v_add_lshl_u32 v202, v199, v195, 1
	v_lshl_add_u64 v[16:17], s[42:43], 0, v[124:125]
	v_readlane_b32 s5, v248, 10
	s_waitcnt vmcnt(1)
	v_lshlrev_b32_e32 v66, 16, v10
	v_and_b32_e32 v67, 0xffff0000, v10
	s_waitcnt vmcnt(0)
; template <bool TRACK> ...
;     ...
;       float qv[4][8]; float ss = 0.f;
; #pragma unroll
;       for (int d = 0; d < 4; ++d) { unpack8(*(const u32x4*)(qp + d * 16), qv[d]);
; #pragma unroll
;           for (int e = 0; e < 8; ++e) ss += qv[d][e] * qv[d][e]; }
;       ss += __shfl_xor(ss, 32);
;       const float rs = rsqrtf(ss * (1.0f / 64.0f) + 1e-6f) * (0.125f * LOG2E);
; #pragma unroll
;       for (int d = 0; d < 4; ++d) { const f32x4 w0 = *(const f32x4*)(qnw + d * 16 + hi * 8), w1 = *(const f32x4*)(qnw + d * 16 + hi * 8 + 4);
;           qv[d][0] *= rs * w0.x; qv[d][1] *= rs * w0.y; qv[d][2] *= rs * w0.z; qv[d][3] *= rs * w0.w; qv[d][4] *= rs * w1.x; qv[d][5] *= rs * w1.y; qv[d][6] *= rs * w1.z; qv[d][7] *= rs * w1.w; }
;       if (tpos0 >= 0) { const float* cp = ropet + (size_t)(tpos0 + qrow) * 32 + hi * 8; const float* sp = cp + 2048 * 32;
; #pragma unroll
;           for (int ax = 0; ax < 2; ++ax) { const f32x4 c0 = *(const f32x4*)(cp + ax * 16), c1 = *(const f32x4*)(cp + ax * 16 + 4), s0_ = *(const f32x4*)(sp + ax * 16), s1_ = *(const f32x4*)(sp + ax * 16 + 4);
;               const float cc[8] = {c0.x, c0.y, c0.z, c0.w, c1.x, c1.y, c1.z, c1.w}, sn[8] = {s0_.x, s0_.y, s0_.z, s0_.w, s1_.x, s1_.y, s1_.z, s1_.w};
; #pragma unroll
;               for (int e = 0; e < 8; ++e) { const float xa = qv[2 * ax][e], xb = qv[2 * ax + 1][e]; qv[2 * ax][e] = xa * cc[e] - xb * sn[e]; qv[2 * ax + 1][e] = xb * cc[e] + xa * sn[e]; } } }
	v_lshlrev_b32_e32 v64, 16, v18
	v_and_b32_e32 v65, 0xffff0000, v18
	v_lshlrev_b32_e32 v62, 16, v11
	v_and_b32_e32 v63, 0xffff0000, v11
	v_lshlrev_b32_e32 v60, 16, v19
	v_and_b32_e32 v61, 0xffff0000, v19
	v_lshlrev_b32_e32 v58, 16, v12
	v_and_b32_e32 v59, 0xffff0000, v12
	v_lshlrev_b32_e32 v56, 16, v20
	v_and_b32_e32 v57, 0xffff0000, v20
	v_lshlrev_b32_e32 v54, 16, v13
	v_and_b32_e32 v55, 0xffff0000, v13
	v_lshlrev_b32_e32 v24, 16, v21
	v_and_b32_e32 v25, 0xffff0000, v21
	global_load_dwordx4 v[10:13], v[26:27], off offset:64
	global_load_dwordx4 v[18:21], v[26:27], off offset:96
	v_pk_mul_f32 v[28:29], v[66:67], v[66:67]
	v_pk_mul_f32 v[30:31], v[62:63], v[62:63]
	v_add_f32_e32 v28, v28, v29
	v_add_f32_e32 v28, v30, v28
	v_pk_mul_f32 v[32:33], v[58:59], v[58:59]
	v_add_f32_e32 v28, v31, v28
	v_add_f32_e32 v28, v32, v28
	v_pk_mul_f32 v[44:45], v[54:55], v[54:55]
	v_add_f32_e32 v28, v33, v28
	v_add_f32_e32 v28, v44, v28
	v_pk_mul_f32 v[68:69], v[64:65], v[64:65]
	v_add_f32_e32 v28, v45, v28
	v_add_f32_e32 v28, v68, v28
	v_pk_mul_f32 v[70:71], v[60:61], v[60:61]
	v_add_f32_e32 v28, v69, v28
	v_add_f32_e32 v28, v70, v28
	v_pk_mul_f32 v[72:73], v[56:57], v[56:57]
	v_add_f32_e32 v28, v71, v28
	v_add_f32_e32 v28, v72, v28
	v_pk_mul_f32 v[74:75], v[24:25], v[24:25]
	v_add_f32_e32 v28, v73, v28
	v_add_f32_e32 v28, v74, v28
	v_add_f32_e32 v28, v75, v28
	v_add_u32_e32 v45, 0, v201
	s_waitcnt vmcnt(1)
	v_lshlrev_b32_e32 v50, 16, v10
	v_and_b32_e32 v51, 0xffff0000, v10
	v_pk_mul_f32 v[26:27], v[50:51], v[50:51]
	v_lshlrev_b32_e32 v46, 16, v11
	v_and_b32_e32 v47, 0xffff0000, v11
	v_add_f32_e32 v26, v26, v28
	v_pk_mul_f32 v[10:11], v[46:47], v[46:47]
	v_add_f32_e32 v26, v27, v26
	v_lshlrev_b32_e32 v38, 16, v12
	v_and_b32_e32 v39, 0xffff0000, v12
	v_add_f32_e32 v10, v10, v26
	s_waitcnt vmcnt(0)
	v_lshlrev_b32_e32 v52, 16, v18
	v_and_b32_e32 v53, 0xffff0000, v18
	v_lshlrev_b32_e32 v48, 16, v19
	v_and_b32_e32 v49, 0xffff0000, v19
	v_pk_mul_f32 v[18:19], v[38:39], v[38:39]
	v_add_f32_e32 v10, v11, v10
	v_lshlrev_b32_e32 v34, 16, v13
	v_and_b32_e32 v35, 0xffff0000, v13
	v_add_f32_e32 v10, v18, v10
	v_pk_mul_f32 v[12:13], v[34:35], v[34:35]
	v_add_f32_e32 v10, v19, v10
	v_add_f32_e32 v10, v12, v10
	v_lshlrev_b32_e32 v40, 16, v20
	v_and_b32_e32 v41, 0xffff0000, v20
	v_lshlrev_b32_e32 v36, 16, v21
	v_and_b32_e32 v37, 0xffff0000, v21
	v_pk_mul_f32 v[20:21], v[52:53], v[52:53]
	v_add_f32_e32 v10, v13, v10
	v_add_f32_e32 v10, v20, v10
	v_pk_mul_f32 v[76:77], v[48:49], v[48:49]
	v_add_f32_e32 v10, v21, v10
	v_add_f32_e32 v10, v76, v10
	v_pk_mul_f32 v[78:79], v[40:41], v[40:41]
	v_add_f32_e32 v10, v77, v10
	v_add_f32_e32 v10, v78, v10
	v_pk_mul_f32 v[80:81], v[36:37], v[36:37]
	v_add_f32_e32 v10, v79, v10
	v_add_f32_e32 v10, v80, v10
	v_add_f32_e32 v18, v81, v10
	global_load_dwordx4 v[10:13], v124, s[42:43] offset:208
	v_add_u32_e32 v19, 0, v203
	v_and_b32_e32 v20, 0x1f8, v190
	v_add_u32_e32 v71, 0x2400, v19
	v_lshlrev_b32_e32 v44, 4, v20
	s_and_saveexec_b64 s[20:21], s[4:5]
	s_xor_b64 s[48:49], exec, s[20:21]
	s_cbranch_execz .LBB0_165
	ds_bpermute_b32 v19, v188, v18
	s_mov_b32 s4, 0x800000
	s_add_i32 s20, s51, s73
	s_and_b32 s20, s20, 0x1fff
	s_mul_i32 s22, s20, 0x48000
	s_waitcnt lgkmcnt(0)
	v_add_f32_e32 v18, v18, v19
	v_fmamk_f32 v18, v18, 0x3c800000, v163
	v_cmp_gt_f32_e32 vcc, s4, v18
	v_mul_f32_e32 v19, 0x4b800000, v18
	s_add_u32 s20, s50, s22
	v_cndmask_b32_e32 v18, v18, v19, vcc
	v_rsq_f32_e32 v18, v18
	s_addc_u32 s21, 0, 0
	v_readlane_b32 s4, v250, 63
	v_readlane_b32 s5, v249, 0
	v_mul_f32_e32 v19, 0x45800000, v18
	v_cndmask_b32_e32 v18, v18, v19, vcc
	v_mul_f32_e32 v68, 0x3e38aa3b, v18
	global_load_dwordx4 v[72:75], v[16:17], off offset:16
	global_load_dwordx4 v[26:29], v[16:17], off
	global_load_dwordx4 v[76:79], v[16:17], off offset:80
	global_load_dwordx4 v[30:33], v[16:17], off offset:64
	global_load_dwordx4 v[18:21], v[16:17], off offset:144
	global_load_dwordx4 v[80:83], v[16:17], off offset:128
	global_load_dwordx4 v[84:87], v[16:17], off offset:192
	global_load_dwordx4 v[88:91], v[22:23], off offset:16
	global_load_dwordx4 v[92:95], v[22:23], off
	global_load_dwordx4 v[96:99], v[14:15], off offset:16
	s_nop 0
	global_load_dwordx4 v[14:17], v[14:15], off
	s_waitcnt vmcnt(11)
	v_pk_mul_f32 v[10:11], v[10:11], v[68:69] op_sel_hi:[1,0]
	v_pk_mul_f32 v[12:13], v[12:13], v[68:69] op_sel_hi:[1,0]
	v_pk_mul_f32 v[40:41], v[10:11], v[40:41]
	v_pk_mul_f32 v[12:13], v[12:13], v[36:37]
	v_mov_b32_e32 v123, 0
	s_waitcnt vmcnt(9)
	v_pk_mul_f32 v[26:27], v[26:27], v[68:69] op_sel_hi:[1,0]
	s_nop 0
	v_pk_mul_f32 v[66:67], v[26:27], v[66:67]
	s_waitcnt vmcnt(7)
	v_pk_mul_f32 v[26:27], v[30:31], v[68:69] op_sel_hi:[1,0]
	s_waitcnt vmcnt(6)
	v_pk_mul_f32 v[10:11], v[18:19], v[68:69] op_sel_hi:[1,0]
	v_pk_mul_f32 v[30:31], v[26:27], v[64:65]
	v_pk_mul_f32 v[18:19], v[10:11], v[38:39]
	s_waitcnt vmcnt(0)
	v_pk_mul_f32 v[26:27], v[14:15], v[30:31]
	v_pk_mul_f32 v[30:31], v[92:93], v[30:31]
	v_pk_fma_f32 v[26:27], v[92:93], v[66:67], v[26:27] neg_lo:[0,0,1] neg_hi:[0,0,1]
	v_pk_fma_f32 v[30:31], v[14:15], v[66:67], v[30:31]
	v_pk_mul_f32 v[14:15], v[28:29], v[68:69] op_sel_hi:[1,0]
	v_pk_mul_f32 v[28:29], v[32:33], v[68:69] op_sel_hi:[1,0]
	v_pk_mul_f32 v[14:15], v[14:15], v[62:63]
	v_pk_mul_f32 v[32:33], v[28:29], v[60:61]
	v_cvt_pk_bf16_f32 v106, v30, v31
	v_pk_mul_f32 v[28:29], v[16:17], v[32:33]
	v_pk_mul_f32 v[32:33], v[94:95], v[32:33]
	v_pk_fma_f32 v[28:29], v[94:95], v[14:15], v[28:29] neg_lo:[0,0,1] neg_hi:[0,0,1]
	v_pk_fma_f32 v[60:61], v[16:17], v[14:15], v[32:33]
	v_pk_mul_f32 v[16:17], v[76:77], v[68:69] op_sel_hi:[1,0]
	v_pk_mul_f32 v[14:15], v[72:73], v[68:69] op_sel_hi:[1,0]
	v_pk_mul_f32 v[16:17], v[16:17], v[56:57]
	v_pk_mul_f32 v[14:15], v[14:15], v[58:59]
	v_pk_mul_f32 v[32:33], v[96:97], v[16:17]
	v_pk_mul_f32 v[16:17], v[88:89], v[16:17]
	v_pk_fma_f32 v[32:33], v[88:89], v[14:15], v[32:33] neg_lo:[0,0,1] neg_hi:[0,0,1]
	v_pk_fma_f32 v[56:57], v[96:97], v[14:15], v[16:17]
	v_pk_mul_f32 v[16:17], v[78:79], v[68:69] op_sel_hi:[1,0]
	v_pk_mul_f32 v[14:15], v[74:75], v[68:69] op_sel_hi:[1,0]
	v_pk_mul_f32 v[16:17], v[16:17], v[24:25]
	v_pk_mul_f32 v[14:15], v[14:15], v[54:55]
	v_pk_mul_f32 v[24:25], v[98:99], v[16:17]
	v_pk_mul_f32 v[16:17], v[90:91], v[16:17]
	v_pk_fma_f32 v[54:55], v[90:91], v[14:15], v[24:25] neg_lo:[0,0,1] neg_hi:[0,0,1]
	v_pk_fma_f32 v[58:59], v[98:99], v[14:15], v[16:17]
	global_load_dwordx4 v[14:17], v[22:23], off offset:80
	global_load_dwordx4 v[62:65], v[22:23], off offset:64
	s_nop 0
	global_load_dwordx4 v[22:25], v[42:43], off offset:16
	global_load_dwordx4 v[72:75], v[42:43], off
	v_pk_mul_f32 v[42:43], v[80:81], v[68:69] op_sel_hi:[1,0]
	s_nop 0
	v_pk_mul_f32 v[50:51], v[42:43], v[50:51]
	v_pk_mul_f32 v[42:43], v[84:85], v[68:69] op_sel_hi:[1,0]
	s_barrier
; #define LAS __attribute__((address_space(3)))
; __device__ __forceinline__ unsigned pk2(float lo, float hi) { f32x2_t v = {lo, hi}; bf16x2_t b = __builtin_convertvector(v, bf16x2_t); return __builtin_bit_cast(unsigned, b); }
; template <bool TRACK> ...
;     ...
;               for (int e = 0; e < 8; ++e) { const float xa = qv[2 * ax][e], xb = qv[2 * ax + 1][e]; qv[2 * ax][e] = xa * cc[e] - xb * sn[e]; qv[2 * ax + 1][e] = xb * cc[e] + xa * sn[e]; } } }
; #pragma unroll
;       for (int d = 0; d < 4; ++d) { u32x4 w; w.x = pk2(qv[d][0], qv[d][1]); w.y = pk2(qv[d][2], qv[d][3]); w.z = pk2(qv[d][4], qv[d][5]); w.w = pk2(qv[d][6], qv[d][7]); qf[d] = __builtin_bit_cast(bf16x8, w); } }
;     __syncthreads();
;     *(LAS u32x4*)(lds + (srow * 72 + sc * 8) * 2) = kreg; { LAS u32x2* vw_ = (LAS u32x2*)(lds + 9216 + (srow * 68 + sc * 8) * 2); vw_[0] = (u32x2){vreg.x, vreg.y}; vw_[1] = (u32x2){vreg.z, vreg.w}; }
;     __syncthreads();
;     f32x16 o0, o1;
; #pragma unroll
;     for (int r = 0; r < 16; ++r) { o0[r] = 0.f; o1[r] = 0.f; }
;     float m = m_init, lsum = hi == 0 ? l_init : 0.f;
;     f32x16 negm, lacc;
; #pragma unroll
;     for (int r = 0; r < 16; ++r) { negm[r] = TRACK ? -m_init : 0.f; lacc[r] = TRACK ? 0.f : l_init * __builtin_amdgcn_exp2f(m_init); }
;     const bf16x8 ones = __builtin_bit_cast(bf16x8, ((u32x4){0x3f803f80u, 0x3f803f80u, 0x3f803f80u, 0x3f803f80u}));
	v_pk_mul_f32 v[52:53], v[42:43], v[52:53]
	ds_write_b128 v45, v[2:5]
	ds_write2_b64 v71, v[6:7], v[8:9] offset1:1
	v_mov_b32_e32 v45, v1
	v_lshl_add_u64 v[2:3], s[20:21], 0, v[44:45]
	s_add_u32 s20, s45, s22
	v_lshl_add_u64 v[2:3], v[2:3], 0, v[134:135]
	s_addc_u32 s21, 0, 0
	v_lshl_add_u64 v[158:159], s[4:5], 0, v[2:3]
	v_lshl_add_u64 v[2:3], s[20:21], 0, v[134:135]
	v_readlane_b32 s4, v249, 1
	v_lshl_add_u64 v[2:3], v[2:3], 0, v[0:1]
	v_readlane_b32 s5, v249, 2
	v_cvt_pk_bf16_f32 v110, v26, v27
	v_cvt_pk_bf16_f32 v111, v28, v29
	v_cvt_pk_bf16_f32 v112, v32, v33
	v_lshl_add_u64 v[160:161], s[4:5], 0, v[2:3]
	v_mov_b32_e32 v0, v1
	v_mov_b32_e32 v2, v1
	v_mov_b32_e32 v3, v1
	v_mov_b32_e32 v4, v1
	v_mov_b32_e32 v5, v1
	v_mov_b32_e32 v6, v1
	v_mov_b32_e32 v7, v1
	v_mov_b32_e32 v8, v1
	v_mov_b32_e32 v9, v1
	v_cvt_pk_bf16_f32 v107, v60, v61
	v_cvt_pk_bf16_f32 v108, v56, v57
	v_cvt_pk_bf16_f32 v109, v58, v59
	v_cvt_pk_bf16_f32 v113, v54, v55
	s_mov_b32 s20, 0
	s_waitcnt lgkmcnt(0)
	s_barrier
	s_waitcnt vmcnt(1)
	v_pk_mul_f32 v[10:11], v[40:41], v[22:23]
	s_waitcnt vmcnt(0)
	v_pk_mul_f32 v[42:43], v[52:53], v[72:73]
	v_pk_fma_f32 v[10:11], v[18:19], v[14:15], v[10:11] neg_lo:[0,0,1] neg_hi:[0,0,1]
	v_pk_fma_f32 v[42:43], v[50:51], v[62:63], v[42:43] neg_lo:[0,0,1] neg_hi:[0,0,1]
	v_pk_mul_f32 v[50:51], v[50:51], v[72:73]
	v_pk_mul_f32 v[18:19], v[18:19], v[22:23]
	v_pk_fma_f32 v[50:51], v[52:53], v[62:63], v[50:51]
	v_pk_mul_f32 v[52:53], v[82:83], v[68:69] op_sel_hi:[1,0]
	v_pk_fma_f32 v[14:15], v[40:41], v[14:15], v[18:19]
	v_pk_mul_f32 v[18:19], v[20:21], v[68:69] op_sel_hi:[1,0]
	v_pk_mul_f32 v[52:53], v[52:53], v[46:47]
	v_pk_mul_f32 v[46:47], v[86:87], v[68:69] op_sel_hi:[1,0]
	v_pk_mul_f32 v[18:19], v[18:19], v[34:35]
	v_pk_mul_f32 v[20:21], v[12:13], v[24:25]
	v_pk_mul_f32 v[48:49], v[46:47], v[48:49]
	v_pk_fma_f32 v[20:21], v[18:19], v[16:17], v[20:21] neg_lo:[0,0,1] neg_hi:[0,0,1]
	v_pk_mul_f32 v[18:19], v[18:19], v[24:25]
	v_pk_mul_f32 v[46:47], v[48:49], v[74:75]
	v_pk_fma_f32 v[12:13], v[12:13], v[16:17], v[18:19]
	v_cvt_pk_bf16_f32 v100, v14, v15
	v_mov_b32_e32 v14, v1
	v_mov_b32_e32 v15, v1
	v_pk_fma_f32 v[46:47], v[52:53], v[64:65], v[46:47] neg_lo:[0,0,1] neg_hi:[0,0,1]
	v_pk_mul_f32 v[52:53], v[52:53], v[74:75]
	v_cvt_pk_bf16_f32 v101, v12, v13
	v_cvt_pk_bf16_f32 v104, v10, v11
	v_cvt_pk_bf16_f32 v105, v20, v21
	v_mov_b32_e32 v10, v1
	v_mov_b32_e32 v11, v1
	v_mov_b32_e32 v12, v1
	v_mov_b32_e32 v13, v1
	v_mov_b64_e32 v[32:33], v[14:15]
	v_pk_fma_f32 v[48:49], v[48:49], v[64:65], v[52:53]
	v_cvt_pk_bf16_f32 v98, v50, v51
	v_bfrev_b32_e32 v50, 1
	v_mov_b64_e32 v[30:31], v[12:13]
	v_mov_b64_e32 v[28:29], v[10:11]
	v_mov_b64_e32 v[26:27], v[8:9]
	v_mov_b64_e32 v[24:25], v[6:7]
	v_mov_b64_e32 v[22:23], v[4:5]
	v_mov_b64_e32 v[20:21], v[2:3]
	v_mov_b64_e32 v[18:19], v[0:1]
	v_mov_b64_e32 v[16:17], v[14:15]
	v_cvt_pk_bf16_f32 v99, v48, v49
	v_cvt_pk_bf16_f32 v102, v42, v43
	v_cvt_pk_bf16_f32 v103, v46, v47
	v_mov_b64_e32 v[14:15], v[12:13]
	v_mov_b64_e32 v[12:13], v[10:11]
	v_mov_b64_e32 v[10:11], v[8:9]
	v_mov_b64_e32 v[8:9], v[6:7]
	v_mov_b64_e32 v[6:7], v[4:5]
	v_mov_b64_e32 v[4:5], v[2:3]
	v_mov_b64_e32 v[2:3], v[0:1]
	v_mov_b32_e32 v0, 0
	v_mov_b32_e32 v51, v50
	v_mov_b32_e32 v52, v50
	v_mov_b32_e32 v53, v50
	v_mov_b32_e32 v54, v50
	v_mov_b32_e32 v55, v50
	v_mov_b32_e32 v56, v50
	v_mov_b32_e32 v57, v50
	v_mov_b32_e32 v58, v50
	v_mov_b32_e32 v59, v50
	v_mov_b32_e32 v60, v50
	v_mov_b32_e32 v61, v50
	v_mov_b32_e32 v62, v50
	v_mov_b32_e32 v63, v50
	v_mov_b32_e32 v64, v50
	v_mov_b32_e32 v65, v50
	s_branch .LBB0_160
